# attention softmax: xor-32 ds_bpermute exchanges (row max, row sum) replaced by v_permlane32_swap (no LDS round trip)
# baseline (speedup 1.0000x reference)
.LBB0_239:
	s_barrier
	ds_write_b128 v104, v[44:47]
	ds_write_b128 v106, v[40:43]
	ds_write_b16 v101, v36 offset:8192
	ds_write_b16_d16_hi v102, v36 offset:8328
	ds_write_b16 v101, v37 offset:8464
	ds_write_b16_d16_hi v102, v37 offset:8600
	ds_write_b16 v101, v38 offset:8736
	ds_write_b16_d16_hi v102, v38 offset:8872
	ds_write_b16 v101, v39 offset:9008
	ds_write_b16_d16_hi v102, v39 offset:9144
	ds_write_b16 v101, v32 offset:9280
	ds_write_b16_d16_hi v102, v32 offset:9416
	ds_write_b16 v101, v33 offset:9552
	ds_write_b16_d16_hi v102, v33 offset:9688
	ds_write_b16 v101, v34 offset:9824
	ds_write_b16_d16_hi v102, v34 offset:9960
	ds_write_b16 v101, v35 offset:10096
	ds_write_b16_d16_hi v102, v35 offset:10232
	s_waitcnt lgkmcnt(0)
	s_barrier
	ds_read_b128 v[32:35], v107
	ds_read_b128 v[48:51], v107 offset:4096
	s_waitcnt lgkmcnt(1)
	v_mfma_f32_32x32x16_bf16 v[32:47], v[32:35], v[72:75], 0
	ds_read_b128 v[114:117], v108
	ds_read_b128 v[118:121], v108 offset:4096
	s_mov_b32 s6, 0x3e000000
	s_mov_b32 s1, 0xf149f2ca
	v_add_u32_e32 v135, 0x2000, v111
	s_add_i32 s5, s5, 64
	s_cmpk_lg_i32 s5, 0x100
	s_waitcnt lgkmcnt(2)
	v_mfma_f32_32x32x16_bf16 v[48:63], v[48:51], v[72:75], 0
	s_waitcnt lgkmcnt(1)
	v_mfma_f32_32x32x16_bf16 v[32:47], v[114:117], v[64:67], v[32:47]
	ds_read_b128 v[114:117], v109 offset:4096
	s_waitcnt lgkmcnt(1)
	v_mfma_f32_32x32x16_bf16 v[48:63], v[118:121], v[64:67], v[48:63]
	s_waitcnt lgkmcnt(0)
	v_mfma_f32_32x32x16_bf16 v[48:63], v[114:117], v[68:71], v[48:63]
	ds_read_b128 v[114:117], v110 offset:4096
	s_waitcnt lgkmcnt(0)
	v_mfma_f32_32x32x16_bf16 v[48:63], v[114:117], v[76:79], v[48:63]
	ds_read_b128 v[114:117], v109
	ds_read_b128 v[118:121], v110
	s_waitcnt lgkmcnt(1)
	v_mfma_f32_32x32x16_bf16 v[32:47], v[114:117], v[68:71], v[32:47]
	s_nop 7
	v_mul_f32_e64 v48, v48, s6
	v_mul_f32_e64 v49, v49, s6
	v_mul_f32_e64 v50, v50, s6
	v_mul_f32_e64 v51, v51, s6
	v_mul_f32_e64 v52, v52, s6
	v_mul_f32_e64 v53, v53, s6
	v_pk_mul_f32 v[54:55], v[54:55], s[6:7] op_sel_hi:[1,0]
	v_pk_mul_f32 v[56:57], v[56:57], s[6:7] op_sel_hi:[1,0]
	v_pk_mul_f32 v[58:59], v[58:59], s[6:7] op_sel_hi:[1,0]
	v_pk_mul_f32 v[60:61], v[60:61], s[6:7] op_sel_hi:[1,0]
	s_waitcnt lgkmcnt(0)
	v_mfma_f32_32x32x16_bf16 v[32:47], v[118:121], v[76:79], v[32:47]
	v_mul_f32_e64 v62, v62, s6
	v_mul_f32_e64 v63, v63, s6
	s_nop 9
	v_pk_mul_f32 v[114:115], v[32:33], s[6:7] op_sel_hi:[1,0]
	v_pk_mul_f32 v[34:35], v[34:35], s[6:7] op_sel_hi:[1,0]
	v_max3_f32 v32, v114, s1, v115
	v_pk_mul_f32 v[36:37], v[36:37], s[6:7] op_sel_hi:[1,0]
	v_max3_f32 v32, v32, v34, v35
	v_pk_mul_f32 v[38:39], v[38:39], s[6:7] op_sel_hi:[1,0]
	v_max3_f32 v32, v32, v36, v37
	v_pk_mul_f32 v[40:41], v[40:41], s[6:7] op_sel_hi:[1,0]
	v_max3_f32 v32, v32, v38, v39
	v_pk_mul_f32 v[42:43], v[42:43], s[6:7] op_sel_hi:[1,0]
	v_max3_f32 v32, v32, v40, v41
	v_pk_mul_f32 v[44:45], v[44:45], s[6:7] op_sel_hi:[1,0]
	v_max3_f32 v32, v32, v42, v43
	v_pk_mul_f32 v[46:47], v[46:47], s[6:7] op_sel_hi:[1,0]
	v_max3_f32 v32, v32, v44, v45
	v_max3_f32 v32, v32, v46, v47
	v_max3_f32 v32, v32, v48, v49
	v_max3_f32 v32, v32, v50, v51
	v_max3_f32 v32, v32, v52, v53
	v_max3_f32 v32, v32, v54, v55
	v_max3_f32 v32, v32, v56, v57
	v_max3_f32 v32, v32, v58, v59
	v_max3_f32 v32, v32, v60, v61
	v_max3_f32 v32, v32, v62, v63
	v_mov_b32_e32 v33, v32
	s_nop 1
	v_permlane32_swap_b32_e32 v33, v32
	s_nop 0
	v_cmp_lt_f32_e32 vcc, s86, v115
	s_waitcnt lgkmcnt(0)
	v_max3_f32 v33, v112, v32, v33
	v_sub_f32_e32 v113, v115, v33
	v_sub_f32_e32 v32, v112, v33
	v_sub_f32_e32 v112, v114, v33
	v_mul_f32_e32 v113, 0x3fb8aa3b, v113
	v_exp_f32_e32 v113, v113
	v_mul_f32_e32 v112, 0x3fb8aa3b, v112
	v_sub_f32_e32 v116, v35, v33
	v_exp_f32_e32 v112, v112
	v_sub_f32_e32 v115, v34, v33
	v_mul_f32_e32 v116, 0x3fb8aa3b, v116
	v_exp_f32_e32 v116, v116
	v_mul_f32_e32 v115, 0x3fb8aa3b, v115
	v_exp_f32_e32 v115, v115
	v_cndmask_b32_e32 v113, 0, v113, vcc
	v_cmp_lt_f32_e32 vcc, s86, v114
	v_mul_f32_e32 v32, 0x3fb8aa3b, v32
	v_exp_f32_e32 v32, v32
	v_cndmask_b32_e32 v112, 0, v112, vcc
	v_cmp_lt_f32_e32 vcc, s86, v35
	v_add_f32_e32 v114, 0, v112
	v_add_f32_e32 v114, v113, v114
	v_cndmask_b32_e32 v116, 0, v116, vcc
	v_cmp_lt_f32_e32 vcc, s86, v34
	v_sub_f32_e32 v35, v36, v33
	v_mul_f32_e32 v35, 0x3fb8aa3b, v35
	v_cndmask_b32_e32 v115, 0, v115, vcc
	v_add_f32_e32 v34, v115, v114
	v_sub_f32_e32 v114, v37, v33
	v_mul_f32_e32 v114, 0x3fb8aa3b, v114
	v_exp_f32_e32 v114, v114
	v_exp_f32_e32 v35, v35
	v_cmp_lt_f32_e32 vcc, s86, v37
	v_add_f32_e32 v34, v116, v34
	v_pk_mul_f32 v[30:31], v[30:31], v[32:33] op_sel_hi:[1,0]
	v_cndmask_b32_e32 v114, 0, v114, vcc
	v_cmp_lt_f32_e32 vcc, s86, v36
	v_sub_f32_e32 v36, v39, v33
	v_mul_f32_e32 v36, 0x3fb8aa3b, v36
	v_cndmask_b32_e32 v117, 0, v35, vcc
	v_sub_f32_e32 v35, v38, v33
	v_exp_f32_e32 v36, v36
	v_mul_f32_e32 v35, 0x3fb8aa3b, v35
	v_exp_f32_e32 v35, v35
	v_cmp_lt_f32_e32 vcc, s86, v39
	v_add_f32_e32 v34, v117, v34
	v_add_f32_e32 v34, v114, v34
	v_cndmask_b32_e32 v118, 0, v36, vcc
	v_cmp_lt_f32_e32 vcc, s86, v38
	v_sub_f32_e32 v36, v41, v33
	v_mul_f32_e32 v36, 0x3fb8aa3b, v36
	v_cndmask_b32_e32 v119, 0, v35, vcc
	v_sub_f32_e32 v35, v40, v33
	v_exp_f32_e32 v36, v36
	v_mul_f32_e32 v35, 0x3fb8aa3b, v35
	v_exp_f32_e32 v35, v35
	v_cmp_lt_f32_e32 vcc, s86, v41
	v_add_f32_e32 v34, v119, v34
	v_add_f32_e32 v34, v118, v34
	v_cndmask_b32_e32 v120, 0, v36, vcc
	v_cmp_lt_f32_e32 vcc, s86, v40
	v_sub_f32_e32 v36, v43, v33
	v_mul_f32_e32 v36, 0x3fb8aa3b, v36
	v_cndmask_b32_e32 v121, 0, v35, vcc
	v_sub_f32_e32 v35, v42, v33
	v_exp_f32_e32 v36, v36
	v_mul_f32_e32 v35, 0x3fb8aa3b, v35
	v_exp_f32_e32 v35, v35
	v_cmp_lt_f32_e32 vcc, s86, v43
	v_add_f32_e32 v34, v121, v34
	v_add_f32_e32 v34, v120, v34
	v_cndmask_b32_e32 v122, 0, v36, vcc
	v_cmp_lt_f32_e32 vcc, s86, v42
	v_sub_f32_e32 v36, v45, v33
	v_mul_f32_e32 v36, 0x3fb8aa3b, v36
	v_cndmask_b32_e32 v123, 0, v35, vcc
	v_sub_f32_e32 v35, v44, v33
	v_exp_f32_e32 v36, v36
	v_mul_f32_e32 v35, 0x3fb8aa3b, v35
	v_exp_f32_e32 v35, v35
	v_cmp_lt_f32_e32 vcc, s86, v45
	v_add_f32_e32 v34, v123, v34
	v_add_f32_e32 v34, v122, v34
	v_cndmask_b32_e32 v124, 0, v36, vcc
	v_cmp_lt_f32_e32 vcc, s86, v44
	v_sub_f32_e32 v36, v47, v33
	v_mul_f32_e32 v36, 0x3fb8aa3b, v36
	v_cndmask_b32_e32 v125, 0, v35, vcc
	v_sub_f32_e32 v35, v46, v33
	v_exp_f32_e32 v36, v36
	v_mul_f32_e32 v35, 0x3fb8aa3b, v35
	v_exp_f32_e32 v35, v35
	v_cmp_lt_f32_e32 vcc, s86, v47
	v_add_f32_e32 v34, v125, v34
	v_add_f32_e32 v34, v124, v34
	v_cndmask_b32_e32 v47, 0, v36, vcc
	v_cmp_lt_f32_e32 vcc, s86, v46
	v_sub_f32_e32 v36, v49, v33
	v_mul_f32_e32 v36, 0x3fb8aa3b, v36
	v_cndmask_b32_e32 v46, 0, v35, vcc
	v_sub_f32_e32 v35, v48, v33
	v_exp_f32_e32 v36, v36
	v_mul_f32_e32 v35, 0x3fb8aa3b, v35
	v_exp_f32_e32 v35, v35
	v_cmp_lt_f32_e32 vcc, s86, v49
	v_add_f32_e32 v34, v46, v34
	v_add_f32_e32 v34, v47, v34
	v_cndmask_b32_e32 v49, 0, v36, vcc
	v_cmp_lt_f32_e32 vcc, s86, v48
	v_sub_f32_e32 v36, v51, v33
	v_mul_f32_e32 v36, 0x3fb8aa3b, v36
	v_cndmask_b32_e32 v48, 0, v35, vcc
	v_sub_f32_e32 v35, v50, v33
	v_exp_f32_e32 v36, v36
	v_mul_f32_e32 v35, 0x3fb8aa3b, v35
	v_exp_f32_e32 v35, v35
	v_cmp_lt_f32_e32 vcc, s86, v51
	v_add_f32_e32 v34, v48, v34
	v_add_f32_e32 v34, v49, v34
	v_cndmask_b32_e32 v51, 0, v36, vcc
	v_cmp_lt_f32_e32 vcc, s86, v50
	v_sub_f32_e32 v36, v53, v33
	v_mul_f32_e32 v36, 0x3fb8aa3b, v36
	v_cndmask_b32_e32 v50, 0, v35, vcc
	v_sub_f32_e32 v35, v52, v33
	v_exp_f32_e32 v36, v36
	v_mul_f32_e32 v35, 0x3fb8aa3b, v35
	v_exp_f32_e32 v35, v35
	v_cmp_lt_f32_e32 vcc, s86, v53
	v_add_f32_e32 v34, v50, v34
	v_add_f32_e32 v34, v51, v34
	v_cndmask_b32_e32 v53, 0, v36, vcc
	v_cmp_lt_f32_e32 vcc, s86, v52
	v_sub_f32_e32 v36, v55, v33
	v_mul_f32_e32 v36, 0x3fb8aa3b, v36
	v_cndmask_b32_e32 v52, 0, v35, vcc
	v_sub_f32_e32 v35, v54, v33
	v_exp_f32_e32 v36, v36
	v_mul_f32_e32 v35, 0x3fb8aa3b, v35
	v_exp_f32_e32 v35, v35
	v_cmp_lt_f32_e32 vcc, s86, v55
	v_add_f32_e32 v34, v52, v34
	v_add_f32_e32 v34, v53, v34
	v_cndmask_b32_e32 v55, 0, v36, vcc
	v_cmp_lt_f32_e32 vcc, s86, v54
	v_sub_f32_e32 v36, v57, v33
	v_mul_f32_e32 v36, 0x3fb8aa3b, v36
	v_cndmask_b32_e32 v54, 0, v35, vcc
	v_sub_f32_e32 v35, v56, v33
	v_exp_f32_e32 v36, v36
	v_mul_f32_e32 v35, 0x3fb8aa3b, v35
	v_exp_f32_e32 v35, v35
	v_cmp_lt_f32_e32 vcc, s86, v57
	v_add_f32_e32 v34, v54, v34
	v_add_f32_e32 v34, v55, v34
	v_cndmask_b32_e32 v57, 0, v36, vcc
	v_cmp_lt_f32_e32 vcc, s86, v56
	v_sub_f32_e32 v36, v59, v33
	v_mul_f32_e32 v36, 0x3fb8aa3b, v36
	v_cndmask_b32_e32 v56, 0, v35, vcc
	v_sub_f32_e32 v35, v58, v33
	v_exp_f32_e32 v36, v36
	v_mul_f32_e32 v35, 0x3fb8aa3b, v35
	v_exp_f32_e32 v35, v35
	v_cmp_lt_f32_e32 vcc, s86, v59
	v_add_f32_e32 v34, v56, v34
	v_add_f32_e32 v34, v57, v34
	v_cndmask_b32_e32 v59, 0, v36, vcc
	v_cmp_lt_f32_e32 vcc, s86, v58
	v_cvt_pk_bf16_f32 v38, v112, v113
	v_add_u32_e32 v112, 0x3000, v111
	v_cndmask_b32_e32 v58, 0, v35, vcc
	v_add_f32_e32 v34, v58, v34
	v_add_f32_e32 v126, v59, v34
	v_sub_f32_e32 v34, v60, v33
	v_mul_f32_e32 v127, 0x3fb8aa3b, v34
	ds_read2_b64 v[34:37], v135 offset1:2
	ds_read2_b64 v[42:45], v112 offset0:32 offset1:34
	v_pk_mul_f32 v[28:29], v[28:29], v[32:33] op_sel_hi:[1,0]
	v_pk_mul_f32 v[26:27], v[26:27], v[32:33] op_sel_hi:[1,0]
	v_pk_mul_f32 v[24:25], v[24:25], v[32:33] op_sel_hi:[1,0]
	v_pk_mul_f32 v[22:23], v[22:23], v[32:33] op_sel_hi:[1,0]
	v_pk_mul_f32 v[20:21], v[20:21], v[32:33] op_sel_hi:[1,0]
	v_pk_mul_f32 v[18:19], v[18:19], v[32:33] op_sel_hi:[1,0]
	v_pk_mul_f32 v[16:17], v[16:17], v[32:33] op_sel_hi:[1,0]
	v_cvt_pk_bf16_f32 v39, v115, v116
	v_cvt_pk_bf16_f32 v40, v117, v114
	v_cvt_pk_bf16_f32 v41, v119, v118
	v_sub_f32_e32 v134, v61, v33
	v_pk_mul_f32 v[14:15], v[14:15], v[32:33] op_sel_hi:[1,0]
	s_waitcnt lgkmcnt(1)
	v_mfma_f32_32x32x16_bf16 v[16:31], v[34:37], v[38:41], v[16:31]
	ds_read2_b64 v[34:37], v135 offset0:4 offset1:6
	v_mul_f32_e64 v12, v12, v32
	v_mul_f32_e64 v13, v13, v32
	v_mul_f32_e64 v10, v10, v32
	v_mul_f32_e64 v11, v11, v32
	v_pk_mul_f32 v[8:9], v[8:9], v[32:33] op_sel_hi:[1,0]
	v_pk_mul_f32 v[6:7], v[6:7], v[32:33] op_sel_hi:[1,0]
	v_pk_mul_f32 v[4:5], v[4:5], v[32:33] op_sel_hi:[1,0]
	v_pk_mul_f32 v[2:3], v[2:3], v[32:33] op_sel_hi:[1,0]
	v_pk_mul_f32 v[0:1], v[0:1], v[32:33] op_sel_hi:[1,0]
	v_cmp_lt_f32_e32 vcc, s86, v61
	v_sub_f32_e32 v61, v62, v33
	s_waitcnt lgkmcnt(1)
	v_mfma_f32_32x32x16_bf16 v[0:15], v[42:45], v[38:41], v[0:15]
	v_mul_f32_e32 v38, 0x3fb8aa3b, v134
	v_exp_f32_e32 v113, v38
	v_cvt_pk_bf16_f32 v38, v121, v120
	v_cvt_pk_bf16_f32 v39, v123, v122
	v_cvt_pk_bf16_f32 v40, v125, v124
	v_cvt_pk_bf16_f32 v41, v46, v47
	ds_read2_b64 v[42:45], v112 offset0:36 offset1:38
	v_cndmask_b32_e32 v46, 0, v113, vcc
	s_waitcnt lgkmcnt(1)
	v_mfma_f32_32x32x16_bf16 v[16:31], v[34:37], v[38:41], v[16:31]
	v_exp_f32_e32 v34, v127
	v_cmp_lt_f32_e32 vcc, s86, v60
	s_nop 1
	v_cndmask_b32_e32 v47, 0, v34, vcc
	ds_read2_b64 v[34:37], v135 offset0:8 offset1:10
	v_cmp_lt_f32_e32 vcc, s86, v63
	s_waitcnt lgkmcnt(1)
	v_mfma_f32_32x32x16_bf16 v[0:15], v[42:45], v[38:41], v[0:15]
	ds_read2_b64 v[42:45], v112 offset0:40 offset1:42
	v_cvt_pk_bf16_f32 v38, v48, v49
	v_cvt_pk_bf16_f32 v39, v50, v51
	v_cvt_pk_bf16_f32 v40, v52, v53
	v_cvt_pk_bf16_f32 v41, v54, v55
	v_add_f32_e32 v60, v47, v126
	v_add_f32_e32 v60, v46, v60
	s_waitcnt lgkmcnt(1)
	v_mfma_f32_32x32x16_bf16 v[16:31], v[34:37], v[38:41], v[16:31]
	v_sub_f32_e32 v34, v63, v33
	v_mul_f32_e32 v34, 0x3fb8aa3b, v34
	v_exp_f32_e32 v34, v34
	v_mul_f32_e32 v35, 0x3fb8aa3b, v61
	v_exp_f32_e32 v48, v35
	v_cndmask_b32_e32 v49, 0, v34, vcc
	s_waitcnt lgkmcnt(0)
	v_mfma_f32_32x32x16_bf16 v[0:15], v[42:45], v[38:41], v[0:15]
	ds_read2_b64 v[34:37], v135 offset0:12 offset1:14
	ds_read2_b64 v[42:45], v112 offset0:44 offset1:46
	v_cmp_lt_f32_e32 vcc, s86, v62
	v_cvt_pk_bf16_f32 v38, v56, v57
	v_cvt_pk_bf16_f32 v39, v58, v59
	v_cndmask_b32_e32 v41, 0, v48, vcc
	v_add_f32_e32 v48, v41, v60
	v_cvt_pk_bf16_f32 v40, v47, v46
	v_cvt_pk_bf16_f32 v41, v41, v49
	s_waitcnt lgkmcnt(1)
	s_nop 0
	v_mfma_f32_32x32x16_bf16 v[16:31], v[34:37], v[38:41], v[16:31]
	v_add_f32_e32 v34, v49, v48
	v_mov_b32_e32 v35, v34
	s_nop 1
	v_permlane32_swap_b32_e32 v35, v34
	s_nop 0
	s_waitcnt lgkmcnt(0)
	v_add_f32_e32 v34, v34, v35
	v_mfma_f32_32x32x16_bf16 v[0:15], v[42:45], v[38:41], v[0:15]
	v_fmac_f32_e32 v34, v105, v32
	s_cbranch_scc1 .LBB0_237
	v_max_f32_e32 v32, v99, v99
	v_max_f32_e32 v35, v33, v33
	v_max_f32_e32 v32, v35, v32
	v_sub_f32_e32 v33, v33, v32
	v_sub_f32_e32 v32, v99, v32
	v_mul_f32_e32 v33, 0x3fb8aa3b, v33
	v_mul_f32_e32 v32, 0x3fb8aa3b, v32
	v_exp_f32_e32 v33, v33
	v_exp_f32_e32 v32, v32
	s_lshl_b32 s92, s4, 1
	v_lshlrev_b32_e32 v128, 3, v98
	v_fmac_f32_e32 v32, v33, v34
	v_div_scale_f32 v34, s[0:1], v32, v32, v33
	v_rcp_f32_e32 v35, v34
	v_readlane_b32 s0, v254, 43
	v_readlane_b32 s1, v254, 44
	v_fma_f32 v36, -v34, v35, 1.0
	v_fmac_f32_e32 v35, v36, v35
	v_div_scale_f32 v36, vcc, v33, v32, v33
	v_mul_f32_e32 v37, v36, v35
	v_fma_f32 v38, -v34, v37, v36
	v_fmac_f32_e32 v37, v38, v35
	v_fma_f32 v34, -v34, v37, v36
	v_div_fmas_f32 v34, v34, v35, v37
	v_div_fixup_f32 v32, v34, v32, v33
	v_lshlrev_b64 v[34:35], 11, v[96:97]
	v_lshl_add_u64 v[34:35], s[0:1], 0, v[34:35]
	v_lshl_add_u64 v[34:35], v[34:35], 0, s[92:93]
	v_pk_mul_f32 v[16:17], v[16:17], v[32:33] op_sel_hi:[1,0]
	v_pk_mul_f32 v[18:19], v[18:19], v[32:33] op_sel_hi:[1,0]
	v_cvt_pk_bf16_f32 v16, v16, v17
	v_cvt_pk_bf16_f32 v17, v18, v19
	v_lshl_add_u64 v[18:19], v[34:35], 0, v[128:129]
	s_mov_b64 s[0:1], 0x153ca600
	v_lshl_add_u64 v[34:35], v[18:19], 0, s[0:1]
	s_mov_b32 s0, 0x153ca000
	v_add_co_u32_e32 v18, vcc, s0, v18
	v_pk_mul_f32 v[0:1], v[0:1], v[32:33] op_sel_hi:[1,0]
	v_pk_mul_f32 v[2:3], v[2:3], v[32:33] op_sel_hi:[1,0]
	v_addc_co_u32_e32 v19, vcc, 0, v19, vcc
	v_cvt_pk_bf16_f32 v0, v0, v1
	v_cvt_pk_bf16_f32 v1, v2, v3
	global_store_dwordx2 v[18:19], v[16:17], off offset:1536
	v_pk_mul_f32 v[16:17], v[20:21], v[32:33] op_sel_hi:[1,0]
	v_pk_mul_f32 v[18:19], v[22:23], v[32:33] op_sel_hi:[1,0]
	global_store_dwordx2 v[34:35], v[0:1], off offset:64
	v_pk_mul_f32 v[0:1], v[4:5], v[32:33] op_sel_hi:[1,0]
	v_pk_mul_f32 v[2:3], v[6:7], v[32:33] op_sel_hi:[1,0]
	v_cvt_pk_bf16_f32 v16, v16, v17
	v_cvt_pk_bf16_f32 v17, v18, v19
	v_cvt_pk_bf16_f32 v0, v0, v1
	v_cvt_pk_bf16_f32 v1, v2, v3
	global_store_dwordx2 v[34:35], v[16:17], off offset:16
	v_pk_mul_f32 v[16:17], v[24:25], v[32:33] op_sel_hi:[1,0]
	v_pk_mul_f32 v[18:19], v[26:27], v[32:33] op_sel_hi:[1,0]
	global_store_dwordx2 v[34:35], v[0:1], off offset:80
	v_pk_mul_f32 v[0:1], v[8:9], v[32:33] op_sel_hi:[1,0]
	v_pk_mul_f32 v[2:3], v[10:11], v[32:33] op_sel_hi:[1,0]
	v_cvt_pk_bf16_f32 v16, v16, v17
	v_cvt_pk_bf16_f32 v17, v18, v19
	v_cvt_pk_bf16_f32 v0, v0, v1
	v_cvt_pk_bf16_f32 v1, v2, v3
	global_store_dwordx2 v[34:35], v[16:17], off offset:32
	v_pk_mul_f32 v[16:17], v[28:29], v[32:33] op_sel_hi:[1,0]
	v_pk_mul_f32 v[18:19], v[30:31], v[32:33] op_sel_hi:[1,0]
	global_store_dwordx2 v[34:35], v[0:1], off offset:96
	v_pk_mul_f32 v[0:1], v[12:13], v[32:33] op_sel_hi:[1,0]
	v_pk_mul_f32 v[2:3], v[14:15], v[32:33] op_sel_hi:[1,0]
	v_cvt_pk_bf16_f32 v16, v16, v17
	v_cvt_pk_bf16_f32 v17, v18, v19
	v_cvt_pk_bf16_f32 v0, v0, v1
	v_cvt_pk_bf16_f32 v1, v2, v3
	global_store_dwordx2 v[34:35], v[16:17], off offset:48
	global_store_dwordx2 v[34:35], v[0:1], off offset:112
	s_barrier
	s_mov_b64 s[0:1], 0

.LBB0_245:
	s_barrier
	ds_write_b128 v104, v[44:47]
	ds_write_b128 v105, v[40:43]
	ds_write_b16 v102, v36 offset:8192
	ds_write_b16_d16_hi v103, v36 offset:8328
	ds_write_b16 v102, v37 offset:8464
	ds_write_b16_d16_hi v103, v37 offset:8600
	ds_write_b16 v102, v38 offset:8736
	ds_write_b16_d16_hi v103, v38 offset:8872
	ds_write_b16 v102, v39 offset:9008
	ds_write_b16_d16_hi v103, v39 offset:9144
	ds_write_b16 v102, v32 offset:9280
	ds_write_b16_d16_hi v103, v32 offset:9416
	ds_write_b16 v102, v33 offset:9552
	ds_write_b16_d16_hi v103, v33 offset:9688
	ds_write_b16 v102, v34 offset:9824
	ds_write_b16_d16_hi v103, v34 offset:9960
	ds_write_b16 v102, v35 offset:10096
	ds_write_b16_d16_hi v103, v35 offset:10232
	s_waitcnt lgkmcnt(0)
	s_barrier
	ds_read_b128 v[32:35], v106
	ds_read_b128 v[48:51], v106 offset:4096
	s_waitcnt lgkmcnt(1)
	v_mfma_f32_32x32x16_bf16 v[32:47], v[32:35], v[64:67], 0
	ds_read_b128 v[114:117], v108
	ds_read_b128 v[118:121], v108 offset:4096
	s_mov_b32 s6, 0x3e000000
	s_mov_b32 s5, 0xf149f2ca
	v_add_u32_e32 v134, 0x2000, v111
	s_add_u32 s0, s0, 0x74000
	s_addc_u32 s1, s1, 0
	s_cmp_lg_u32 s0, 0x1d0000
	s_waitcnt lgkmcnt(2)
	v_mfma_f32_32x32x16_bf16 v[48:63], v[48:51], v[64:67], 0
	s_waitcnt lgkmcnt(1)
	v_mfma_f32_32x32x16_bf16 v[32:47], v[114:117], v[68:71], v[32:47]
	ds_read_b128 v[114:117], v109 offset:4096
	s_waitcnt lgkmcnt(1)
	v_mfma_f32_32x32x16_bf16 v[48:63], v[118:121], v[68:71], v[48:63]
	s_waitcnt lgkmcnt(0)
	v_mfma_f32_32x32x16_bf16 v[48:63], v[114:117], v[72:75], v[48:63]
	ds_read_b128 v[114:117], v110 offset:4096
	s_waitcnt lgkmcnt(0)
	v_mfma_f32_32x32x16_bf16 v[48:63], v[114:117], v[76:79], v[48:63]
	ds_read_b128 v[114:117], v109
	ds_read_b128 v[118:121], v110
	s_waitcnt lgkmcnt(1)
	v_mfma_f32_32x32x16_bf16 v[32:47], v[114:117], v[72:75], v[32:47]
	s_nop 7
	v_mul_f32_e64 v48, v48, s6
	v_mul_f32_e64 v49, v49, s6
	v_mul_f32_e64 v50, v50, s6
	v_mul_f32_e64 v51, v51, s6
	v_mul_f32_e64 v52, v52, s6
	v_mul_f32_e64 v53, v53, s6
	v_pk_mul_f32 v[54:55], v[54:55], s[6:7] op_sel_hi:[1,0]
	v_pk_mul_f32 v[56:57], v[56:57], s[6:7] op_sel_hi:[1,0]
	v_pk_mul_f32 v[58:59], v[58:59], s[6:7] op_sel_hi:[1,0]
	v_pk_mul_f32 v[60:61], v[60:61], s[6:7] op_sel_hi:[1,0]
	s_waitcnt lgkmcnt(0)
	v_mfma_f32_32x32x16_bf16 v[32:47], v[118:121], v[76:79], v[32:47]
	v_mul_f32_e64 v62, v62, s6
	v_mul_f32_e64 v63, v63, s6
	s_nop 9
	v_pk_mul_f32 v[114:115], v[32:33], s[6:7] op_sel_hi:[1,0]
	v_pk_mul_f32 v[34:35], v[34:35], s[6:7] op_sel_hi:[1,0]
	v_max3_f32 v32, v114, s5, v115
	v_pk_mul_f32 v[36:37], v[36:37], s[6:7] op_sel_hi:[1,0]
	v_max3_f32 v32, v32, v34, v35
	v_pk_mul_f32 v[38:39], v[38:39], s[6:7] op_sel_hi:[1,0]
	v_max3_f32 v32, v32, v36, v37
	v_pk_mul_f32 v[40:41], v[40:41], s[6:7] op_sel_hi:[1,0]
	v_max3_f32 v32, v32, v38, v39
	v_pk_mul_f32 v[42:43], v[42:43], s[6:7] op_sel_hi:[1,0]
	v_max3_f32 v32, v32, v40, v41
	v_pk_mul_f32 v[44:45], v[44:45], s[6:7] op_sel_hi:[1,0]
	v_max3_f32 v32, v32, v42, v43
	v_pk_mul_f32 v[46:47], v[46:47], s[6:7] op_sel_hi:[1,0]
	v_max3_f32 v32, v32, v44, v45
	v_max3_f32 v32, v32, v46, v47
	v_max3_f32 v32, v32, v48, v49
	v_max3_f32 v32, v32, v50, v51
	v_max3_f32 v32, v32, v52, v53
	v_max3_f32 v32, v32, v54, v55
	v_max3_f32 v32, v32, v56, v57
	v_max3_f32 v32, v32, v58, v59
	v_max3_f32 v32, v32, v60, v61
	v_max3_f32 v32, v32, v62, v63
	v_mov_b32_e32 v33, v32
	s_nop 1
	v_permlane32_swap_b32_e32 v33, v32
	s_nop 0
	v_cmp_lt_f32_e32 vcc, s86, v115
	s_waitcnt lgkmcnt(0)
	v_max3_f32 v33, v112, v32, v33
	v_sub_f32_e32 v113, v115, v33
	v_sub_f32_e32 v32, v112, v33
	v_sub_f32_e32 v112, v114, v33
	v_mul_f32_e32 v113, 0x3fb8aa3b, v113
	v_exp_f32_e32 v113, v113
	v_mul_f32_e32 v112, 0x3fb8aa3b, v112
	v_sub_f32_e32 v116, v35, v33
	v_exp_f32_e32 v112, v112
	v_sub_f32_e32 v115, v34, v33
	v_mul_f32_e32 v116, 0x3fb8aa3b, v116
	v_exp_f32_e32 v116, v116
	v_mul_f32_e32 v115, 0x3fb8aa3b, v115
	v_exp_f32_e32 v115, v115
	v_cndmask_b32_e32 v113, 0, v113, vcc
	v_cmp_lt_f32_e32 vcc, s86, v114
	v_mul_f32_e32 v32, 0x3fb8aa3b, v32
	v_exp_f32_e32 v32, v32
	v_cndmask_b32_e32 v112, 0, v112, vcc
	v_cmp_lt_f32_e32 vcc, s86, v35
	v_add_f32_e32 v114, 0, v112
	v_add_f32_e32 v114, v113, v114
	v_cndmask_b32_e32 v116, 0, v116, vcc
	v_cmp_lt_f32_e32 vcc, s86, v34
	v_sub_f32_e32 v35, v36, v33
	v_mul_f32_e32 v35, 0x3fb8aa3b, v35
	v_cndmask_b32_e32 v115, 0, v115, vcc
	v_add_f32_e32 v34, v115, v114
	v_sub_f32_e32 v114, v37, v33
	v_mul_f32_e32 v114, 0x3fb8aa3b, v114
	v_exp_f32_e32 v114, v114
	v_exp_f32_e32 v35, v35
	v_cmp_lt_f32_e32 vcc, s86, v37
	v_add_f32_e32 v34, v116, v34
	v_pk_mul_f32 v[30:31], v[30:31], v[32:33] op_sel_hi:[1,0]
	v_cndmask_b32_e32 v114, 0, v114, vcc
	v_cmp_lt_f32_e32 vcc, s86, v36
	v_sub_f32_e32 v36, v39, v33
	v_mul_f32_e32 v36, 0x3fb8aa3b, v36
	v_cndmask_b32_e32 v117, 0, v35, vcc
	v_sub_f32_e32 v35, v38, v33
	v_exp_f32_e32 v36, v36
	v_mul_f32_e32 v35, 0x3fb8aa3b, v35
	v_exp_f32_e32 v35, v35
	v_cmp_lt_f32_e32 vcc, s86, v39
	v_add_f32_e32 v34, v117, v34
	v_add_f32_e32 v34, v114, v34
	v_cndmask_b32_e32 v118, 0, v36, vcc
	v_cmp_lt_f32_e32 vcc, s86, v38
	v_sub_f32_e32 v36, v41, v33
	v_mul_f32_e32 v36, 0x3fb8aa3b, v36
	v_cndmask_b32_e32 v119, 0, v35, vcc
	v_sub_f32_e32 v35, v40, v33
	v_exp_f32_e32 v36, v36
	v_mul_f32_e32 v35, 0x3fb8aa3b, v35
	v_exp_f32_e32 v35, v35
	v_cmp_lt_f32_e32 vcc, s86, v41
	v_add_f32_e32 v34, v119, v34
	v_add_f32_e32 v34, v118, v34
	v_cndmask_b32_e32 v120, 0, v36, vcc
	v_cmp_lt_f32_e32 vcc, s86, v40
	v_sub_f32_e32 v36, v43, v33
	v_mul_f32_e32 v36, 0x3fb8aa3b, v36
	v_cndmask_b32_e32 v121, 0, v35, vcc
	v_sub_f32_e32 v35, v42, v33
	v_exp_f32_e32 v36, v36
	v_mul_f32_e32 v35, 0x3fb8aa3b, v35
	v_exp_f32_e32 v35, v35
	v_cmp_lt_f32_e32 vcc, s86, v43
	v_add_f32_e32 v34, v121, v34
	v_add_f32_e32 v34, v120, v34
	v_cndmask_b32_e32 v122, 0, v36, vcc
	v_cmp_lt_f32_e32 vcc, s86, v42
	v_sub_f32_e32 v36, v45, v33
	v_mul_f32_e32 v36, 0x3fb8aa3b, v36
	v_cndmask_b32_e32 v123, 0, v35, vcc
	v_sub_f32_e32 v35, v44, v33
	v_exp_f32_e32 v36, v36
	v_mul_f32_e32 v35, 0x3fb8aa3b, v35
	v_exp_f32_e32 v35, v35
	v_cmp_lt_f32_e32 vcc, s86, v45
	v_add_f32_e32 v34, v123, v34
	v_add_f32_e32 v34, v122, v34
	v_cndmask_b32_e32 v124, 0, v36, vcc
	v_cmp_lt_f32_e32 vcc, s86, v44
	v_sub_f32_e32 v36, v47, v33
	v_mul_f32_e32 v36, 0x3fb8aa3b, v36
	v_cndmask_b32_e32 v125, 0, v35, vcc
	v_sub_f32_e32 v35, v46, v33
	v_exp_f32_e32 v36, v36
	v_mul_f32_e32 v35, 0x3fb8aa3b, v35
	v_exp_f32_e32 v35, v35
	v_cmp_lt_f32_e32 vcc, s86, v47
	v_add_f32_e32 v34, v125, v34
	v_add_f32_e32 v34, v124, v34
	v_cndmask_b32_e32 v47, 0, v36, vcc
	v_cmp_lt_f32_e32 vcc, s86, v46
	v_sub_f32_e32 v36, v49, v33
	v_mul_f32_e32 v36, 0x3fb8aa3b, v36
	v_cndmask_b32_e32 v46, 0, v35, vcc
	v_sub_f32_e32 v35, v48, v33
	v_exp_f32_e32 v36, v36
	v_mul_f32_e32 v35, 0x3fb8aa3b, v35
	v_exp_f32_e32 v35, v35
	v_cmp_lt_f32_e32 vcc, s86, v49
	v_add_f32_e32 v34, v46, v34
	v_add_f32_e32 v34, v47, v34
	v_cndmask_b32_e32 v49, 0, v36, vcc
	v_cmp_lt_f32_e32 vcc, s86, v48
	v_sub_f32_e32 v36, v51, v33
	v_mul_f32_e32 v36, 0x3fb8aa3b, v36
	v_cndmask_b32_e32 v48, 0, v35, vcc
	v_sub_f32_e32 v35, v50, v33
	v_exp_f32_e32 v36, v36
	v_mul_f32_e32 v35, 0x3fb8aa3b, v35
	v_exp_f32_e32 v35, v35
	v_cmp_lt_f32_e32 vcc, s86, v51
	v_add_f32_e32 v34, v48, v34
	v_add_f32_e32 v34, v49, v34
	v_cndmask_b32_e32 v51, 0, v36, vcc
	v_cmp_lt_f32_e32 vcc, s86, v50
	v_sub_f32_e32 v36, v53, v33
	v_mul_f32_e32 v36, 0x3fb8aa3b, v36
	v_cndmask_b32_e32 v50, 0, v35, vcc
	v_sub_f32_e32 v35, v52, v33
	v_exp_f32_e32 v36, v36
	v_mul_f32_e32 v35, 0x3fb8aa3b, v35
	v_exp_f32_e32 v35, v35
	v_cmp_lt_f32_e32 vcc, s86, v53
	v_add_f32_e32 v34, v50, v34
	v_add_f32_e32 v34, v51, v34
	v_cndmask_b32_e32 v53, 0, v36, vcc
	v_cmp_lt_f32_e32 vcc, s86, v52
	v_sub_f32_e32 v36, v55, v33
	v_mul_f32_e32 v36, 0x3fb8aa3b, v36
	v_cndmask_b32_e32 v52, 0, v35, vcc
	v_sub_f32_e32 v35, v54, v33
	v_exp_f32_e32 v36, v36
	v_mul_f32_e32 v35, 0x3fb8aa3b, v35
	v_exp_f32_e32 v35, v35
	v_cmp_lt_f32_e32 vcc, s86, v55
	v_add_f32_e32 v34, v52, v34
	v_add_f32_e32 v34, v53, v34
	v_cndmask_b32_e32 v55, 0, v36, vcc
	v_cmp_lt_f32_e32 vcc, s86, v54
	v_sub_f32_e32 v36, v57, v33
	v_mul_f32_e32 v36, 0x3fb8aa3b, v36
	v_cndmask_b32_e32 v54, 0, v35, vcc
	v_sub_f32_e32 v35, v56, v33
	v_exp_f32_e32 v36, v36
	v_mul_f32_e32 v35, 0x3fb8aa3b, v35
	v_exp_f32_e32 v35, v35
	v_cmp_lt_f32_e32 vcc, s86, v57
	v_add_f32_e32 v34, v54, v34
	v_add_f32_e32 v34, v55, v34
	v_cndmask_b32_e32 v57, 0, v36, vcc
	v_cmp_lt_f32_e32 vcc, s86, v56
	v_sub_f32_e32 v36, v59, v33
	v_mul_f32_e32 v36, 0x3fb8aa3b, v36
	v_cndmask_b32_e32 v56, 0, v35, vcc
	v_sub_f32_e32 v35, v58, v33
	v_exp_f32_e32 v36, v36
	v_mul_f32_e32 v35, 0x3fb8aa3b, v35
	v_exp_f32_e32 v35, v35
	v_cmp_lt_f32_e32 vcc, s86, v59
	v_add_f32_e32 v34, v56, v34
	v_add_f32_e32 v34, v57, v34
	v_cndmask_b32_e32 v59, 0, v36, vcc
	v_cmp_lt_f32_e32 vcc, s86, v58
	v_cvt_pk_bf16_f32 v38, v112, v113
	v_add_u32_e32 v112, 0x3000, v111
	v_cndmask_b32_e32 v58, 0, v35, vcc
	v_add_f32_e32 v34, v58, v34
	v_add_f32_e32 v126, v59, v34
	v_sub_f32_e32 v34, v60, v33
	v_mul_f32_e32 v127, 0x3fb8aa3b, v34
	ds_read2_b64 v[34:37], v134 offset1:2
	ds_read2_b64 v[42:45], v112 offset0:32 offset1:34
	v_pk_mul_f32 v[28:29], v[28:29], v[32:33] op_sel_hi:[1,0]
	v_pk_mul_f32 v[26:27], v[26:27], v[32:33] op_sel_hi:[1,0]
	v_pk_mul_f32 v[24:25], v[24:25], v[32:33] op_sel_hi:[1,0]
	v_pk_mul_f32 v[22:23], v[22:23], v[32:33] op_sel_hi:[1,0]
	v_pk_mul_f32 v[20:21], v[20:21], v[32:33] op_sel_hi:[1,0]
	v_pk_mul_f32 v[18:19], v[18:19], v[32:33] op_sel_hi:[1,0]
	v_pk_mul_f32 v[16:17], v[16:17], v[32:33] op_sel_hi:[1,0]
	v_cvt_pk_bf16_f32 v39, v115, v116
	v_cvt_pk_bf16_f32 v40, v117, v114
	v_cvt_pk_bf16_f32 v41, v119, v118
	v_sub_f32_e32 v128, v61, v33
	v_pk_mul_f32 v[14:15], v[14:15], v[32:33] op_sel_hi:[1,0]
	s_waitcnt lgkmcnt(1)
	v_mfma_f32_32x32x16_bf16 v[16:31], v[34:37], v[38:41], v[16:31]
	ds_read2_b64 v[34:37], v134 offset0:4 offset1:6
	v_mul_f32_e64 v12, v12, v32
	v_mul_f32_e64 v13, v13, v32
	v_mul_f32_e64 v10, v10, v32
	v_mul_f32_e64 v11, v11, v32
	v_pk_mul_f32 v[8:9], v[8:9], v[32:33] op_sel_hi:[1,0]
	v_pk_mul_f32 v[6:7], v[6:7], v[32:33] op_sel_hi:[1,0]
	v_pk_mul_f32 v[4:5], v[4:5], v[32:33] op_sel_hi:[1,0]
	v_pk_mul_f32 v[2:3], v[2:3], v[32:33] op_sel_hi:[1,0]
	v_pk_mul_f32 v[0:1], v[0:1], v[32:33] op_sel_hi:[1,0]
	v_cmp_lt_f32_e32 vcc, s86, v61
	v_sub_f32_e32 v61, v62, v33
	s_waitcnt lgkmcnt(1)
	v_mfma_f32_32x32x16_bf16 v[0:15], v[42:45], v[38:41], v[0:15]
	v_mul_f32_e32 v38, 0x3fb8aa3b, v128
	v_exp_f32_e32 v113, v38
	v_cvt_pk_bf16_f32 v38, v121, v120
	v_cvt_pk_bf16_f32 v39, v123, v122
	v_cvt_pk_bf16_f32 v40, v125, v124
	v_cvt_pk_bf16_f32 v41, v46, v47
	ds_read2_b64 v[42:45], v112 offset0:36 offset1:38
	v_cndmask_b32_e32 v46, 0, v113, vcc
	s_waitcnt lgkmcnt(1)
	v_mfma_f32_32x32x16_bf16 v[16:31], v[34:37], v[38:41], v[16:31]
	v_exp_f32_e32 v34, v127
	v_cmp_lt_f32_e32 vcc, s86, v60
	s_nop 1
	v_cndmask_b32_e32 v47, 0, v34, vcc
	ds_read2_b64 v[34:37], v134 offset0:8 offset1:10
	v_cmp_lt_f32_e32 vcc, s86, v63
	s_waitcnt lgkmcnt(1)
	v_mfma_f32_32x32x16_bf16 v[0:15], v[42:45], v[38:41], v[0:15]
	ds_read2_b64 v[42:45], v112 offset0:40 offset1:42
	v_cvt_pk_bf16_f32 v38, v48, v49
	v_cvt_pk_bf16_f32 v39, v50, v51
	v_cvt_pk_bf16_f32 v40, v52, v53
	v_cvt_pk_bf16_f32 v41, v54, v55
	v_add_f32_e32 v60, v47, v126
	v_add_f32_e32 v60, v46, v60
	s_waitcnt lgkmcnt(1)
	v_mfma_f32_32x32x16_bf16 v[16:31], v[34:37], v[38:41], v[16:31]
	v_sub_f32_e32 v34, v63, v33
	v_mul_f32_e32 v34, 0x3fb8aa3b, v34
	v_exp_f32_e32 v34, v34
	v_mul_f32_e32 v35, 0x3fb8aa3b, v61
	v_exp_f32_e32 v48, v35
	v_cndmask_b32_e32 v49, 0, v34, vcc
	s_waitcnt lgkmcnt(0)
	v_mfma_f32_32x32x16_bf16 v[0:15], v[42:45], v[38:41], v[0:15]
	ds_read2_b64 v[34:37], v134 offset0:12 offset1:14
	ds_read2_b64 v[42:45], v112 offset0:44 offset1:46
	v_cmp_lt_f32_e32 vcc, s86, v62
	v_cvt_pk_bf16_f32 v38, v56, v57
	v_cvt_pk_bf16_f32 v39, v58, v59
	v_cndmask_b32_e32 v41, 0, v48, vcc
	v_add_f32_e32 v48, v41, v60
	v_cvt_pk_bf16_f32 v40, v47, v46
	v_cvt_pk_bf16_f32 v41, v41, v49
	s_waitcnt lgkmcnt(1)
	s_nop 0
	v_mfma_f32_32x32x16_bf16 v[16:31], v[34:37], v[38:41], v[16:31]
	v_add_f32_e32 v34, v49, v48
	v_mov_b32_e32 v35, v34
	s_nop 1
	v_permlane32_swap_b32_e32 v35, v34
	s_nop 0
	s_waitcnt lgkmcnt(0)
	v_add_f32_e32 v34, v34, v35
	v_mfma_f32_32x32x16_bf16 v[0:15], v[42:45], v[38:41], v[0:15]
	v_fmac_f32_e32 v34, v107, v32
	s_cbranch_scc1 .LBB0_243
	v_div_scale_f32 v32, s[0:1], v34, v34, 1.0
	v_rcp_f32_e32 v33, v32
	v_div_scale_f32 v35, vcc, 1.0, v34, 1.0
	v_readlane_b32 s0, v254, 43
	v_fma_f32 v36, -v32, v33, 1.0
	v_fmac_f32_e32 v33, v36, v33
	v_mul_f32_e32 v36, v35, v33
	v_fma_f32 v37, -v32, v36, v35
	v_fmac_f32_e32 v36, v37, v33
	v_fma_f32 v32, -v32, v36, v35
	v_div_fmas_f32 v32, v32, v33, v36
	v_div_fixup_f32 v32, v32, v34, 1.0
	v_lshlrev_b64 v[34:35], 11, v[96:97]
	v_readlane_b32 s1, v254, 44
	s_lshl_b32 s92, s4, 1
	v_pk_mul_f32 v[16:17], v[16:17], v[32:33] op_sel_hi:[1,0]
	v_lshl_add_u64 v[34:35], s[0:1], 0, v[34:35]
	v_lshl_add_u64 v[34:35], v[34:35], 0, s[92:93]
	v_pk_mul_f32 v[18:19], v[18:19], v[32:33] op_sel_hi:[1,0]
	v_lshlrev_b32_e32 v128, 3, v100
	v_cvt_pk_bf16_f32 v16, v16, v17
	v_cvt_pk_bf16_f32 v17, v18, v19
	v_lshl_add_u64 v[18:19], v[34:35], 0, v[128:129]
	s_mov_b64 s[0:1], 0x153ca200
	v_lshl_add_u64 v[34:35], v[18:19], 0, s[0:1]
	s_mov_b32 s0, 0x153ca000
	v_add_co_u32_e32 v18, vcc, s0, v18
	v_pk_mul_f32 v[0:1], v[0:1], v[32:33] op_sel_hi:[1,0]
	v_pk_mul_f32 v[2:3], v[2:3], v[32:33] op_sel_hi:[1,0]
	v_addc_co_u32_e32 v19, vcc, 0, v19, vcc
	v_cvt_pk_bf16_f32 v0, v0, v1
	v_cvt_pk_bf16_f32 v1, v2, v3
	global_store_dwordx2 v[18:19], v[16:17], off offset:512
	v_pk_mul_f32 v[16:17], v[20:21], v[32:33] op_sel_hi:[1,0]
	v_pk_mul_f32 v[18:19], v[22:23], v[32:33] op_sel_hi:[1,0]
	global_store_dwordx2 v[34:35], v[0:1], off offset:64
	v_pk_mul_f32 v[0:1], v[4:5], v[32:33] op_sel_hi:[1,0]
	v_pk_mul_f32 v[2:3], v[6:7], v[32:33] op_sel_hi:[1,0]
	v_cvt_pk_bf16_f32 v16, v16, v17
	v_cvt_pk_bf16_f32 v17, v18, v19
	v_cvt_pk_bf16_f32 v0, v0, v1
	v_cvt_pk_bf16_f32 v1, v2, v3
	global_store_dwordx2 v[34:35], v[16:17], off offset:16
	v_pk_mul_f32 v[16:17], v[24:25], v[32:33] op_sel_hi:[1,0]
	v_pk_mul_f32 v[18:19], v[26:27], v[32:33] op_sel_hi:[1,0]
	global_store_dwordx2 v[34:35], v[0:1], off offset:80
	v_pk_mul_f32 v[0:1], v[8:9], v[32:33] op_sel_hi:[1,0]
	v_pk_mul_f32 v[2:3], v[10:11], v[32:33] op_sel_hi:[1,0]
	v_cvt_pk_bf16_f32 v16, v16, v17
	v_cvt_pk_bf16_f32 v17, v18, v19
	v_cvt_pk_bf16_f32 v0, v0, v1
	v_cvt_pk_bf16_f32 v1, v2, v3
	global_store_dwordx2 v[34:35], v[16:17], off offset:32
	v_pk_mul_f32 v[16:17], v[28:29], v[32:33] op_sel_hi:[1,0]
	v_pk_mul_f32 v[18:19], v[30:31], v[32:33] op_sel_hi:[1,0]
	global_store_dwordx2 v[34:35], v[0:1], off offset:96
	v_pk_mul_f32 v[0:1], v[12:13], v[32:33] op_sel_hi:[1,0]
	v_pk_mul_f32 v[2:3], v[14:15], v[32:33] op_sel_hi:[1,0]
	v_cvt_pk_bf16_f32 v16, v16, v17
	v_cvt_pk_bf16_f32 v17, v18, v19
	v_cvt_pk_bf16_f32 v0, v0, v1
	v_cvt_pk_bf16_f32 v1, v2, v3
	global_store_dwordx2 v[34:35], v[16:17], off offset:48
	global_store_dwordx2 v[34:35], v[0:1], off offset:112
	s_barrier

.LBB0_334:
	s_mov_b32 s4, 0xf149f2ca
	v_max3_f32 v32, v147, s4, v146
	v_max3_f32 v32, v32, v119, v145
	v_max3_f32 v32, v32, v51, v52
	v_max3_f32 v32, v32, v48, v50
	v_max3_f32 v32, v32, v49, v53
	v_max3_f32 v32, v32, v54, v55
	v_max3_f32 v32, v32, v56, v57
	v_max3_f32 v32, v32, v58, v59
	v_max3_f32 v32, v32, v60, v61
	v_max3_f32 v32, v32, v62, v150
	v_max3_f32 v32, v32, v151, v153
	v_max3_f32 v32, v32, v149, v152
	v_max3_f32 v32, v32, v63, v148
	v_max3_f32 v32, v32, v41, v42
	v_max3_f32 v32, v32, v39, v45
	v_max3_f32 v32, v32, v46, v154
	v_mov_b32_e32 v33, v32
	s_nop 1
	v_permlane32_swap_b32_e32 v33, v32
	s_nop 0
	v_cmp_lt_f32_e32 vcc, s86, v147
	s_add_i32 s44, s44, 1
	s_movk_i32 s96, 0x101
	v_add_u32_e32 v118, 64, v118
	s_waitcnt lgkmcnt(0)
	v_max3_f32 v33, v144, v32, v33
	v_sub_f32_e32 v34, v147, v33
	v_mul_f32_e32 v34, 0x3fb8aa3b, v34
	v_sub_f32_e32 v36, v146, v33
	v_exp_f32_e32 v34, v34
	v_mul_f32_e32 v36, 0x3fb8aa3b, v36
	v_exp_f32_e32 v36, v36
	v_sub_f32_e32 v32, v144, v33
	v_cndmask_b32_e32 v35, 0, v34, vcc
	v_cmp_lt_f32_e32 vcc, s86, v146
	v_add_f32_e32 v34, 0, v35
	v_mul_f32_e32 v32, 0x3fb8aa3b, v32
	v_cndmask_b32_e32 v38, 0, v36, vcc
	v_sub_f32_e32 v36, v119, v33
	v_mul_f32_e32 v36, 0x3fb8aa3b, v36
	v_exp_f32_e32 v36, v36
	v_cmp_lt_f32_e32 vcc, s86, v119
	v_add_f32_e32 v34, v38, v34
	v_exp_f32_e32 v32, v32
	v_cndmask_b32_e32 v43, 0, v36, vcc
	v_sub_f32_e32 v36, v145, v33
	v_mul_f32_e32 v36, 0x3fb8aa3b, v36
	v_exp_f32_e32 v36, v36
	v_cmp_lt_f32_e32 vcc, s86, v145
	v_add_f32_e32 v34, v43, v34
	v_cvt_pk_bf16_f32 v146, v35, v38
	v_cndmask_b32_e32 v47, 0, v36, vcc
	v_sub_f32_e32 v36, v51, v33
	v_mul_f32_e32 v36, 0x3fb8aa3b, v36
	v_exp_f32_e32 v36, v36
	v_cmp_lt_f32_e32 vcc, s86, v51
	v_add_f32_e32 v34, v47, v34
	v_add_u32_e32 v38, 0x2000, v142
	v_cndmask_b32_e32 v51, 0, v36, vcc
	v_sub_f32_e32 v36, v52, v33
	v_mul_f32_e32 v36, 0x3fb8aa3b, v36
	v_exp_f32_e32 v36, v36
	v_cmp_lt_f32_e32 vcc, s86, v52
	v_add_f32_e32 v34, v51, v34
	v_pk_mul_f32 v[30:31], v[30:31], v[32:33] op_sel_hi:[1,0]
	v_cndmask_b32_e32 v52, 0, v36, vcc
	v_sub_f32_e32 v36, v48, v33
	v_mul_f32_e32 v36, 0x3fb8aa3b, v36
	v_exp_f32_e32 v36, v36
	v_cmp_lt_f32_e32 vcc, s86, v48
	v_add_f32_e32 v34, v52, v34
	v_pk_mul_f32 v[28:29], v[28:29], v[32:33] op_sel_hi:[1,0]
	v_cndmask_b32_e32 v119, 0, v36, vcc
	v_sub_f32_e32 v36, v50, v33
	v_mul_f32_e32 v36, 0x3fb8aa3b, v36
	v_exp_f32_e32 v36, v36
	v_cmp_lt_f32_e32 vcc, s86, v50
	v_add_f32_e32 v34, v119, v34
	v_pk_mul_f32 v[26:27], v[26:27], v[32:33] op_sel_hi:[1,0]
	v_cndmask_b32_e32 v144, 0, v36, vcc
	v_add_f32_e32 v36, v144, v34
	v_sub_f32_e32 v34, v49, v33
	v_mul_f32_e32 v34, 0x3fb8aa3b, v34
	v_exp_f32_e32 v34, v34
	v_cmp_lt_f32_e32 vcc, s86, v49
	v_pk_mul_f32 v[24:25], v[24:25], v[32:33] op_sel_hi:[1,0]
	v_pk_mul_f32 v[22:23], v[22:23], v[32:33] op_sel_hi:[1,0]
	v_cndmask_b32_e32 v34, 0, v34, vcc
	v_add_f32_e32 v37, v34, v36
	v_sub_f32_e32 v36, v53, v33
	v_mul_f32_e32 v36, 0x3fb8aa3b, v36
	v_exp_f32_e32 v36, v36
	v_cmp_lt_f32_e32 vcc, s86, v53
	v_sub_f32_e32 v53, v59, v33
	v_mul_f32_e32 v53, 0x3fb8aa3b, v53
	v_cndmask_b32_e32 v36, 0, v36, vcc
	v_add_f32_e32 v40, v36, v37
	v_sub_f32_e32 v37, v54, v33
	v_mul_f32_e32 v37, 0x3fb8aa3b, v37
	v_exp_f32_e32 v37, v37
	v_cmp_lt_f32_e32 vcc, s86, v54
	v_exp_f32_e32 v53, v53
	v_pk_mul_f32 v[20:21], v[20:21], v[32:33] op_sel_hi:[1,0]
	v_cndmask_b32_e32 v37, 0, v37, vcc
	v_add_f32_e32 v44, v37, v40
	v_sub_f32_e32 v40, v55, v33
	v_mul_f32_e32 v40, 0x3fb8aa3b, v40
	v_exp_f32_e32 v40, v40
	v_cmp_lt_f32_e32 vcc, s86, v55
	v_pk_mul_f32 v[18:19], v[18:19], v[32:33] op_sel_hi:[1,0]
	v_pk_mul_f32 v[16:17], v[16:17], v[32:33] op_sel_hi:[1,0]
	v_cndmask_b32_e32 v40, 0, v40, vcc
	v_add_f32_e32 v48, v40, v44
	v_sub_f32_e32 v44, v56, v33
	v_mul_f32_e32 v44, 0x3fb8aa3b, v44
	v_exp_f32_e32 v44, v44
	v_cmp_lt_f32_e32 vcc, s86, v56
	v_cvt_pk_bf16_f32 v147, v43, v47
	v_add_u32_e32 v47, 0x3000, v142
	v_cndmask_b32_e32 v44, 0, v44, vcc
	v_add_f32_e32 v49, v44, v48
	v_sub_f32_e32 v48, v57, v33
	v_mul_f32_e32 v48, 0x3fb8aa3b, v48
	v_exp_f32_e32 v48, v48
	v_cmp_lt_f32_e32 vcc, s86, v57
	v_sub_f32_e32 v57, v150, v33
	v_mul_f32_e32 v57, 0x3fb8aa3b, v57
	v_cndmask_b32_e32 v48, 0, v48, vcc
	v_add_f32_e32 v50, v48, v49
	v_sub_f32_e32 v49, v58, v33
	v_mul_f32_e32 v49, 0x3fb8aa3b, v49
	v_exp_f32_e32 v49, v49
	v_cmp_lt_f32_e32 vcc, s86, v58
	v_sub_f32_e32 v58, v151, v33
	v_exp_f32_e32 v57, v57
	v_cndmask_b32_e32 v49, 0, v49, vcc
	v_cmp_lt_f32_e32 vcc, s86, v59
	v_add_f32_e32 v50, v49, v50
	v_mul_f32_e32 v58, 0x3fb8aa3b, v58
	v_cndmask_b32_e32 v53, 0, v53, vcc
	v_add_f32_e32 v54, v53, v50
	v_sub_f32_e32 v50, v60, v33
	v_mul_f32_e32 v50, 0x3fb8aa3b, v50
	v_exp_f32_e32 v50, v50
	v_cmp_lt_f32_e32 vcc, s86, v60
	v_sub_f32_e32 v59, v153, v33
	v_exp_f32_e32 v58, v58
	v_cndmask_b32_e32 v50, 0, v50, vcc
	v_add_f32_e32 v55, v50, v54
	v_sub_f32_e32 v54, v61, v33
	v_mul_f32_e32 v54, 0x3fb8aa3b, v54
	v_exp_f32_e32 v54, v54
	v_cmp_lt_f32_e32 vcc, s86, v61
	v_mul_f32_e32 v59, 0x3fb8aa3b, v59
	v_exp_f32_e32 v59, v59
	v_cndmask_b32_e32 v54, 0, v54, vcc
	v_add_f32_e32 v56, v54, v55
	v_sub_f32_e32 v55, v62, v33
	v_mul_f32_e32 v55, 0x3fb8aa3b, v55
	v_exp_f32_e32 v55, v55
	v_cmp_lt_f32_e32 vcc, s86, v62
	v_pk_mul_f32 v[14:15], v[14:15], v[32:33] op_sel_hi:[1,0]
	v_pk_mul_f32 v[12:13], v[12:13], v[32:33] op_sel_hi:[1,0]
	v_cndmask_b32_e32 v55, 0, v55, vcc
	v_cmp_lt_f32_e32 vcc, s86, v150
	v_add_f32_e32 v56, v55, v56
	v_pk_mul_f32 v[10:11], v[10:11], v[32:33] op_sel_hi:[1,0]
	v_cndmask_b32_e32 v57, 0, v57, vcc
	v_cmp_lt_f32_e32 vcc, s86, v151
	v_add_f32_e32 v56, v57, v56
	v_pk_mul_f32 v[8:9], v[8:9], v[32:33] op_sel_hi:[1,0]
	v_cndmask_b32_e32 v58, 0, v58, vcc
	v_cmp_lt_f32_e32 vcc, s86, v153
	v_add_f32_e32 v56, v58, v56
	v_pk_mul_f32 v[6:7], v[6:7], v[32:33] op_sel_hi:[1,0]
	v_cndmask_b32_e32 v60, 0, v59, vcc
	v_sub_f32_e32 v59, v149, v33
	v_mul_f32_e32 v59, 0x3fb8aa3b, v59
	v_exp_f32_e32 v59, v59
	v_cmp_lt_f32_e32 vcc, s86, v149
	v_add_f32_e32 v56, v60, v56
	v_cvt_pk_bf16_f32 v149, v119, v144
	v_cndmask_b32_e32 v61, 0, v59, vcc
	v_sub_f32_e32 v59, v152, v33
	v_mul_f32_e32 v59, 0x3fb8aa3b, v59
	v_exp_f32_e32 v59, v59
	v_cmp_lt_f32_e32 vcc, s86, v152
	v_add_f32_e32 v56, v61, v56
	v_pk_mul_f32 v[4:5], v[4:5], v[32:33] op_sel_hi:[1,0]
	v_cndmask_b32_e32 v62, 0, v59, vcc
	v_add_f32_e32 v59, v62, v56
	v_sub_f32_e32 v56, v63, v33
	v_mul_f32_e32 v56, 0x3fb8aa3b, v56
	v_exp_f32_e32 v56, v56
	v_cmp_lt_f32_e32 vcc, s86, v63
	v_pk_mul_f32 v[2:3], v[2:3], v[32:33] op_sel_hi:[1,0]
	v_pk_mul_f32 v[0:1], v[0:1], v[32:33] op_sel_hi:[1,0]
	v_cndmask_b32_e32 v56, 0, v56, vcc
	v_add_f32_e32 v63, v56, v59
	v_sub_f32_e32 v59, v148, v33
	v_mul_f32_e32 v59, 0x3fb8aa3b, v59
	v_exp_f32_e32 v59, v59
	v_cmp_lt_f32_e32 vcc, s86, v148
	v_cvt_pk_bf16_f32 v148, v51, v52
	v_cvt_pk_bf16_f32 v34, v34, v36
	v_cndmask_b32_e32 v59, 0, v59, vcc
	v_cmp_lt_f32_e32 vcc, s86, v41
	v_sub_f32_e32 v41, v41, v33
	v_mul_f32_e32 v41, 0x3fb8aa3b, v41
	v_exp_f32_e32 v41, v41
	v_add_f32_e32 v63, v59, v63
	v_cvt_pk_bf16_f32 v36, v44, v48
	v_cvt_pk_bf16_f32 v35, v37, v40
	v_cndmask_b32_e32 v41, 0, v41, vcc
	v_cmp_lt_f32_e32 vcc, s86, v42
	v_sub_f32_e32 v42, v42, v33
	v_mul_f32_e32 v42, 0x3fb8aa3b, v42
	v_exp_f32_e32 v42, v42
	v_add_f32_e32 v63, v41, v63
	v_cvt_pk_bf16_f32 v37, v49, v53
	v_add_u32_e32 v124, 31, v124
	v_cndmask_b32_e32 v134, 0, v42, vcc
	v_cmp_lt_f32_e32 vcc, s86, v39
	v_sub_f32_e32 v39, v39, v33
	v_mul_f32_e32 v39, 0x3fb8aa3b, v39
	v_exp_f32_e32 v39, v39
	v_add_f32_e32 v42, v134, v63
	v_add_u32_e32 v125, 64, v125
	s_cmp_lg_u32 s46, s44
	v_cndmask_b32_e32 v63, 0, v39, vcc
	v_add_f32_e32 v39, v63, v42
	v_sub_f32_e32 v42, v45, v33
	v_mul_f32_e32 v42, 0x3fb8aa3b, v42
	v_exp_f32_e32 v42, v42
	v_cmp_lt_f32_e32 vcc, s86, v45
	s_nop 1
	v_cndmask_b32_e32 v135, 0, v42, vcc
	v_sub_f32_e32 v42, v46, v33
	v_mul_f32_e32 v42, 0x3fb8aa3b, v42
	v_exp_f32_e32 v42, v42
	v_cmp_lt_f32_e32 vcc, s86, v46
	v_add_f32_e32 v39, v135, v39
	s_nop 0
	v_cndmask_b32_e32 v46, 0, v42, vcc
	v_sub_f32_e32 v42, v154, v33
	v_cmp_lt_f32_e32 vcc, s86, v154
	v_mul_f32_e32 v42, 0x3fb8aa3b, v42
	ds_read2_b64 v[150:153], v38 offset1:2
	ds_read2_b64 v[154:157], v38 offset0:4 offset1:6
	v_exp_f32_e32 v42, v42
	s_waitcnt lgkmcnt(1)
	v_mfma_f32_32x32x16_bf16 v[16:31], v[150:153], v[146:149], v[16:31]
	ds_read2_b64 v[150:153], v47 offset0:32 offset1:34
	v_add_f32_e32 v39, v46, v39
	v_cndmask_b32_e32 v136, 0, v42, vcc
	v_add_f32_e32 v39, v136, v39
	v_mov_b32_e32 v42, v39
	s_nop 1
	v_permlane32_swap_b32_e32 v42, v39
	s_nop 0
	s_waitcnt lgkmcnt(0)
	v_add_f32_e32 v39, v39, v42
	ds_read2_b64 v[42:45], v47 offset0:36 offset1:38
	v_mfma_f32_32x32x16_bf16 v[0:15], v[150:153], v[146:149], v[0:15]
	v_fmac_f32_e32 v39, v143, v32
	s_waitcnt lgkmcnt(0)
	v_mfma_f32_32x32x16_bf16 v[0:15], v[42:45], v[34:37], v[0:15]
	ds_read2_b64 v[42:45], v38 offset0:8 offset1:10
	v_mfma_f32_32x32x16_bf16 v[16:31], v[154:157], v[34:37], v[16:31]
	v_cvt_pk_bf16_f32 v34, v50, v54
	v_cvt_pk_bf16_f32 v35, v55, v57
	v_cvt_pk_bf16_f32 v36, v58, v60
	v_cvt_pk_bf16_f32 v37, v61, v62
	s_waitcnt lgkmcnt(0)
	s_nop 0
	v_mfma_f32_32x32x16_bf16 v[16:31], v[42:45], v[34:37], v[16:31]
	ds_read2_b64 v[42:45], v47 offset0:40 offset1:42
	s_waitcnt lgkmcnt(0)
	v_mfma_f32_32x32x16_bf16 v[0:15], v[42:45], v[34:37], v[0:15]
	v_cvt_pk_bf16_f32 v35, v41, v134
	ds_read2_b64 v[40:43], v38 offset0:12 offset1:14
	v_cvt_pk_bf16_f32 v34, v56, v59
	v_cvt_pk_bf16_f32 v36, v63, v135
	v_cvt_pk_bf16_f32 v37, v46, v136
	s_waitcnt lgkmcnt(0)
	s_nop 0
	v_mfma_f32_32x32x16_bf16 v[16:31], v[40:43], v[34:37], v[16:31]
	ds_read2_b64 v[40:43], v47 offset0:44 offset1:46
	s_waitcnt lgkmcnt(0)
	v_mfma_f32_32x32x16_bf16 v[0:15], v[40:43], v[34:37], v[0:15]
	s_cbranch_scc0 .LBB0_336
	v_mov_b32_e32 v144, v33
	v_mov_b32_e32 v143, v39
	s_branch .LBB0_262
